# attention unit tail: conv_tile rewritten with all 24 loads prefetched (counted vmcnt), intra-row shuffle hops via DPP instead of ds_bpermute
# baseline (speedup 1.0000x reference)
; __device__ __forceinline__ unsigned cvtpk(float lo, float hi) { f32x2_t v = {lo, hi}; bf16x2_t b = __builtin_convertvector(v, bf16x2_t); return __builtin_bit_cast(unsigned, b); }
; #define LDZ(row, z) do { const bf16x8 c_ = *reinterpret_cast<const bf16x8*>(proj + (long)(row) * LDP + 4096 + c8);     \
;     _Pragma("unroll") for (int e = 0; e < 8; ++e) z[e] = __uint_as_float(((unsigned)(unsigned short)c_[e]) << 16); } while (0)
; __device__ __forceinline__ void conv_tile(const bf16* __restrict__ proj, bf16* __restrict__ cat, const float* __restrict__ cw, long row0, int ch0, int lane) {
;   const int c8 = ch0 + (lane & 15) * 8; const long r0 = row0 + (lane >> 4) * 8;
;   float w0[8], w1[8], w2[8];
; #pragma unroll
;   for (int e = 0; e < 8; ++e) { w0[e] = cw[c8 + e]; w1[e] = cw[1024 + c8 + e]; w2[e] = cw[2048 + c8 + e]; }
;     ...
;   float zp[8], zc[8], zn[8];
;   if ((r0 & (SEQ - 1)) == 0) {
; #pragma unroll
;     for (int e = 0; e < 8; ++e) zp[e] = 0.f;
;   } else LDZ(r0 - 1, zp);
;   LDZ(r0, zc);
; #pragma unroll
;   for (int i = 0; i < 8; ++i) { const long row = r0 + i;
;     if (((row + 1) & (SEQ - 1)) == 0) {
; #pragma unroll
;       for (int e = 0; e < 8; ++e) zn[e] = 0.f;
;     } else LDZ(row + 1, zn);
;     const bf16x8 gb = *reinterpret_cast<const bf16x8*>(proj + row * LDP + 3072 + c8);
;     float y[8];
; #pragma unroll
;     for (int e = 0; e < 8; ++e) y[e] = __uint_as_float(((unsigned)(unsigned short)gb[e]) << 16) * (zp[e] * w0[e] + zc[e] * w1[e] + zn[e] * w2[e]);
;     u32x4 w; w.x = cvtpk(y[0], y[1]); w.y = cvtpk(y[2], y[3]); w.z = cvtpk(y[4], y[5]); w.w = cvtpk(y[6], y[7]);
;     *(u32x4*)(cat + row * LDC + 1024 + c8) = w;
; #pragma unroll
;     for (int e = 0; e < 8; ++e) { zp[e] = zc[e]; zc[e] = zn[e]; }
;   }
.LBB0_242:
	s_cmpk_gt_u32 s31, 0xff
	s_mov_b64 s[20:21], -1
	s_waitcnt lgkmcnt(0)
	s_barrier
	s_cbranch_scc0 .LBB0_248
	v_and_b32_e32 v150, 0x78, v181
	v_and_b32_e32 v151, 24, v180
	v_or_b32_e32 v150, s28, v150
	v_or_b32_e32 v151, s44, v151
	v_lshlrev_b32_e32 v152, 2, v150
	v_mul_u32_u24_e32 v154, 0x3000, v151
	global_load_dwordx4 v[0:3], v152, s[42:43]
	global_load_dwordx4 v[4:7], v152, s[42:43] offset:16
	v_add_u32_e32 v153, 0x1000, v152
	v_lshlrev_b32_e32 v155, 1, v150
	global_load_dwordx4 v[8:11], v153, s[42:43]
	global_load_dwordx4 v[12:15], v153, s[42:43] offset:16
	v_add_u32_e32 v153, 0x2000, v152
	v_and_b32_e32 v159, 0xff8, v151
	global_load_dwordx4 v[16:19], v153, s[42:43]
	global_load_dwordx4 v[20:23], v153, s[42:43] offset:16
	v_cmp_ne_u32_e32 vcc, 0, v159
	v_add_u32_e32 v156, v154, v155
	v_add_u32_e32 v156, 0xfffff000, v156
	v_add_u32_e32 v157, 0x2800, v156
	v_lshlrev_b32_e32 v158, 12, v151
	v_add_u32_e32 v158, v158, v155
	v_mov_b32_e32 v24, 0
	v_mov_b32_e32 v25, 0
	v_mov_b32_e32 v26, 0
	v_mov_b32_e32 v27, 0
	v_mov_b32_e32 v60, 0
	v_mov_b32_e32 v61, 0
	v_mov_b32_e32 v62, 0
	v_mov_b32_e32 v63, 0
	s_and_saveexec_b64 s[20:21], vcc
	global_load_dwordx4 v[24:27], v156, s[66:67]
	s_or_b64 exec, exec, s[20:21]
	v_add_u32_e32 v156, 0x3000, v156
	global_load_dwordx4 v[28:31], v156, s[66:67]
	v_add_u32_e32 v156, 0x3000, v156
	global_load_dwordx4 v[32:35], v156, s[66:67]
	v_add_u32_e32 v159, 8, v151
	v_and_b32_e32 v159, 0xff8, v159
	global_load_dwordx4 v[64:67], v157, s[66:67]
	v_add_u32_e32 v157, 0x3000, v157
	v_add_u32_e32 v156, 0x3000, v156
	global_load_dwordx4 v[36:39], v156, s[66:67]
	global_load_dwordx4 v[68:71], v157, s[66:67]
	v_add_u32_e32 v157, 0x3000, v157
	v_add_u32_e32 v156, 0x3000, v156
	global_load_dwordx4 v[40:43], v156, s[66:67]
	global_load_dwordx4 v[72:75], v157, s[66:67]
	v_add_u32_e32 v157, 0x3000, v157
	v_add_u32_e32 v156, 0x3000, v156
	global_load_dwordx4 v[44:47], v156, s[66:67]
	global_load_dwordx4 v[76:79], v157, s[66:67]
	v_add_u32_e32 v157, 0x3000, v157
	v_add_u32_e32 v156, 0x3000, v156
	global_load_dwordx4 v[48:51], v156, s[66:67]
	global_load_dwordx4 v[80:83], v157, s[66:67]
	v_add_u32_e32 v157, 0x3000, v157
	v_add_u32_e32 v156, 0x3000, v156
	global_load_dwordx4 v[52:55], v156, s[66:67]
	global_load_dwordx4 v[84:87], v157, s[66:67]
	v_add_u32_e32 v157, 0x3000, v157
	v_add_u32_e32 v156, 0x3000, v156
	global_load_dwordx4 v[56:59], v156, s[66:67]
	global_load_dwordx4 v[88:91], v157, s[66:67]
	v_add_u32_e32 v157, 0x3000, v157
	v_add_u32_e32 v156, 0x3000, v156
	v_cmp_ne_u32_e32 vcc, 0, v159
	s_nop 3
	s_and_saveexec_b64 s[20:21], vcc
	global_load_dwordx4 v[60:63], v156, s[66:67]
	s_or_b64 exec, exec, s[20:21]
	global_load_dwordx4 v[92:95], v157, s[66:67]
	s_waitcnt vmcnt(14)
	v_lshlrev_b32_e32 v96, 16, v24
	v_and_b32_e32 v97, 0xffff0000, v24
	v_lshlrev_b32_e32 v98, 16, v25
	v_and_b32_e32 v99, 0xffff0000, v25
	v_lshlrev_b32_e32 v100, 16, v26
	v_and_b32_e32 v101, 0xffff0000, v26
	v_lshlrev_b32_e32 v102, 16, v27
	v_and_b32_e32 v103, 0xffff0000, v27
	v_lshlrev_b32_e32 v104, 16, v28
	v_and_b32_e32 v105, 0xffff0000, v28
	v_lshlrev_b32_e32 v106, 16, v29
	v_and_b32_e32 v107, 0xffff0000, v29
	v_lshlrev_b32_e32 v108, 16, v30
	v_and_b32_e32 v109, 0xffff0000, v30
	v_lshlrev_b32_e32 v110, 16, v31
	v_and_b32_e32 v111, 0xffff0000, v31
	v_lshlrev_b32_e32 v112, 16, v32
	v_and_b32_e32 v113, 0xffff0000, v32
	v_lshlrev_b32_e32 v114, 16, v33
	v_and_b32_e32 v115, 0xffff0000, v33
	v_lshlrev_b32_e32 v116, 16, v34
	v_and_b32_e32 v117, 0xffff0000, v34
	v_lshlrev_b32_e32 v118, 16, v35
	v_and_b32_e32 v119, 0xffff0000, v35
	v_lshlrev_b32_e32 v120, 16, v64
	v_and_b32_e32 v121, 0xffff0000, v64
	v_lshlrev_b32_e32 v122, 16, v65
	v_and_b32_e32 v123, 0xffff0000, v65
	v_lshlrev_b32_e32 v124, 16, v66
	v_and_b32_e32 v125, 0xffff0000, v66
	v_lshlrev_b32_e32 v126, 16, v67
	v_and_b32_e32 v127, 0xffff0000, v67
	v_pk_mul_f32 v[128:129], v[8:9], v[104:105]
	v_pk_mul_f32 v[130:131], v[10:11], v[106:107]
	v_pk_mul_f32 v[132:133], v[12:13], v[108:109]
	v_pk_mul_f32 v[134:135], v[14:15], v[110:111]
	v_pk_fma_f32 v[128:129], v[0:1], v[96:97], v[128:129]
	v_pk_fma_f32 v[130:131], v[2:3], v[98:99], v[130:131]
	v_pk_fma_f32 v[132:133], v[4:5], v[100:101], v[132:133]
	v_pk_fma_f32 v[134:135], v[6:7], v[102:103], v[134:135]
	v_pk_fma_f32 v[128:129], v[16:17], v[112:113], v[128:129]
	v_pk_fma_f32 v[130:131], v[18:19], v[114:115], v[130:131]
	v_pk_fma_f32 v[132:133], v[20:21], v[116:117], v[132:133]
	v_pk_fma_f32 v[134:135], v[22:23], v[118:119], v[134:135]
	v_pk_mul_f32 v[128:129], v[128:129], v[120:121]
	v_pk_mul_f32 v[130:131], v[130:131], v[122:123]
	v_pk_mul_f32 v[132:133], v[132:133], v[124:125]
	v_pk_mul_f32 v[134:135], v[134:135], v[126:127]
	v_cvt_pk_bf16_f32 v136, v128, v129
	v_cvt_pk_bf16_f32 v137, v130, v131
	v_cvt_pk_bf16_f32 v138, v132, v133
	v_cvt_pk_bf16_f32 v139, v134, v135
	global_store_dwordx4 v158, v[136:139], s[68:69] offset:2048
	v_add_u32_e32 v158, 0x1000, v158
	s_waitcnt vmcnt(13)
; __device__ __forceinline__ unsigned cvtpk(float lo, float hi) { f32x2_t v = {lo, hi}; bf16x2_t b = __builtin_convertvector(v, bf16x2_t); return __builtin_bit_cast(unsigned, b); }
; #define LDZ(row, z) do { const bf16x8 c_ = *reinterpret_cast<const bf16x8*>(proj + (long)(row) * LDP + 4096 + c8);     \
;     _Pragma("unroll") for (int e = 0; e < 8; ++e) z[e] = __uint_as_float(((unsigned)(unsigned short)c_[e]) << 16); } while (0)
; __device__ __forceinline__ void conv_tile(const bf16* __restrict__ proj, bf16* __restrict__ cat, const float* __restrict__ cw, long row0, int ch0, int lane) {
;     ...
;   for (int i = 0; i < 8; ++i) { const long row = r0 + i;
;     if (((row + 1) & (SEQ - 1)) == 0) {
; #pragma unroll
;       for (int e = 0; e < 8; ++e) zn[e] = 0.f;
;     } else LDZ(row + 1, zn);
;     const bf16x8 gb = *reinterpret_cast<const bf16x8*>(proj + row * LDP + 3072 + c8);
;     float y[8];
; #pragma unroll
;     for (int e = 0; e < 8; ++e) y[e] = __uint_as_float(((unsigned)(unsigned short)gb[e]) << 16) * (zp[e] * w0[e] + zc[e] * w1[e] + zn[e] * w2[e]);
;     u32x4 w; w.x = cvtpk(y[0], y[1]); w.y = cvtpk(y[2], y[3]); w.z = cvtpk(y[4], y[5]); w.w = cvtpk(y[6], y[7]);
;     *(u32x4*)(cat + row * LDC + 1024 + c8) = w;
; #pragma unroll
;     for (int e = 0; e < 8; ++e) { zp[e] = zc[e]; zc[e] = zn[e]; }
;   }
	v_lshlrev_b32_e32 v96, 16, v36
	v_and_b32_e32 v97, 0xffff0000, v36
	v_lshlrev_b32_e32 v98, 16, v37
	v_and_b32_e32 v99, 0xffff0000, v37
	v_lshlrev_b32_e32 v100, 16, v38
	v_and_b32_e32 v101, 0xffff0000, v38
	v_lshlrev_b32_e32 v102, 16, v39
	v_and_b32_e32 v103, 0xffff0000, v39
	v_lshlrev_b32_e32 v120, 16, v68
	v_and_b32_e32 v121, 0xffff0000, v68
	v_lshlrev_b32_e32 v122, 16, v69
	v_and_b32_e32 v123, 0xffff0000, v69
	v_lshlrev_b32_e32 v124, 16, v70
	v_and_b32_e32 v125, 0xffff0000, v70
	v_lshlrev_b32_e32 v126, 16, v71
	v_and_b32_e32 v127, 0xffff0000, v71
	v_pk_mul_f32 v[128:129], v[8:9], v[112:113]
	v_pk_mul_f32 v[130:131], v[10:11], v[114:115]
	v_pk_mul_f32 v[132:133], v[12:13], v[116:117]
	v_pk_mul_f32 v[134:135], v[14:15], v[118:119]
	v_pk_fma_f32 v[128:129], v[0:1], v[104:105], v[128:129]
	v_pk_fma_f32 v[130:131], v[2:3], v[106:107], v[130:131]
	v_pk_fma_f32 v[132:133], v[4:5], v[108:109], v[132:133]
	v_pk_fma_f32 v[134:135], v[6:7], v[110:111], v[134:135]
	v_pk_fma_f32 v[128:129], v[16:17], v[96:97], v[128:129]
	v_pk_fma_f32 v[130:131], v[18:19], v[98:99], v[130:131]
	v_pk_fma_f32 v[132:133], v[20:21], v[100:101], v[132:133]
	v_pk_fma_f32 v[134:135], v[22:23], v[102:103], v[134:135]
	v_pk_mul_f32 v[128:129], v[128:129], v[120:121]
	v_pk_mul_f32 v[130:131], v[130:131], v[122:123]
	v_pk_mul_f32 v[132:133], v[132:133], v[124:125]
	v_pk_mul_f32 v[134:135], v[134:135], v[126:127]
	v_cvt_pk_bf16_f32 v140, v128, v129
	v_cvt_pk_bf16_f32 v141, v130, v131
	v_cvt_pk_bf16_f32 v142, v132, v133
	v_cvt_pk_bf16_f32 v143, v134, v135
	global_store_dwordx4 v158, v[140:143], s[68:69] offset:2048
	v_add_u32_e32 v158, 0x1000, v158
	s_waitcnt vmcnt(12)
	v_lshlrev_b32_e32 v104, 16, v40
	v_and_b32_e32 v105, 0xffff0000, v40
	v_lshlrev_b32_e32 v106, 16, v41
	v_and_b32_e32 v107, 0xffff0000, v41
	v_lshlrev_b32_e32 v108, 16, v42
	v_and_b32_e32 v109, 0xffff0000, v42
	v_lshlrev_b32_e32 v110, 16, v43
	v_and_b32_e32 v111, 0xffff0000, v43
	v_lshlrev_b32_e32 v120, 16, v72
	v_and_b32_e32 v121, 0xffff0000, v72
	v_lshlrev_b32_e32 v122, 16, v73
	v_and_b32_e32 v123, 0xffff0000, v73
	v_lshlrev_b32_e32 v124, 16, v74
	v_and_b32_e32 v125, 0xffff0000, v74
	v_lshlrev_b32_e32 v126, 16, v75
	v_and_b32_e32 v127, 0xffff0000, v75
	v_pk_mul_f32 v[128:129], v[8:9], v[96:97]
	v_pk_mul_f32 v[130:131], v[10:11], v[98:99]
	v_pk_mul_f32 v[132:133], v[12:13], v[100:101]
	v_pk_mul_f32 v[134:135], v[14:15], v[102:103]
	v_pk_fma_f32 v[128:129], v[0:1], v[112:113], v[128:129]
	v_pk_fma_f32 v[130:131], v[2:3], v[114:115], v[130:131]
	v_pk_fma_f32 v[132:133], v[4:5], v[116:117], v[132:133]
	v_pk_fma_f32 v[134:135], v[6:7], v[118:119], v[134:135]
	v_pk_fma_f32 v[128:129], v[16:17], v[104:105], v[128:129]
	v_pk_fma_f32 v[130:131], v[18:19], v[106:107], v[130:131]
	v_pk_fma_f32 v[132:133], v[20:21], v[108:109], v[132:133]
	v_pk_fma_f32 v[134:135], v[22:23], v[110:111], v[134:135]
	v_pk_mul_f32 v[128:129], v[128:129], v[120:121]
	v_pk_mul_f32 v[130:131], v[130:131], v[122:123]
	v_pk_mul_f32 v[132:133], v[132:133], v[124:125]
	v_pk_mul_f32 v[134:135], v[134:135], v[126:127]
	v_cvt_pk_bf16_f32 v136, v128, v129
	v_cvt_pk_bf16_f32 v137, v130, v131
	v_cvt_pk_bf16_f32 v138, v132, v133
	v_cvt_pk_bf16_f32 v139, v134, v135
	global_store_dwordx4 v158, v[136:139], s[68:69] offset:2048
	v_add_u32_e32 v158, 0x1000, v158
	s_waitcnt vmcnt(11)
	v_lshlrev_b32_e32 v112, 16, v44
	v_and_b32_e32 v113, 0xffff0000, v44
	v_lshlrev_b32_e32 v114, 16, v45
	v_and_b32_e32 v115, 0xffff0000, v45
	v_lshlrev_b32_e32 v116, 16, v46
	v_and_b32_e32 v117, 0xffff0000, v46
	v_lshlrev_b32_e32 v118, 16, v47
	v_and_b32_e32 v119, 0xffff0000, v47
	v_lshlrev_b32_e32 v120, 16, v76
	v_and_b32_e32 v121, 0xffff0000, v76
	v_lshlrev_b32_e32 v122, 16, v77
	v_and_b32_e32 v123, 0xffff0000, v77
	v_lshlrev_b32_e32 v124, 16, v78
	v_and_b32_e32 v125, 0xffff0000, v78
	v_lshlrev_b32_e32 v126, 16, v79
	v_and_b32_e32 v127, 0xffff0000, v79
	v_pk_mul_f32 v[128:129], v[8:9], v[104:105]
	v_pk_mul_f32 v[130:131], v[10:11], v[106:107]
	v_pk_mul_f32 v[132:133], v[12:13], v[108:109]
	v_pk_mul_f32 v[134:135], v[14:15], v[110:111]
	v_pk_fma_f32 v[128:129], v[0:1], v[96:97], v[128:129]
	v_pk_fma_f32 v[130:131], v[2:3], v[98:99], v[130:131]
	v_pk_fma_f32 v[132:133], v[4:5], v[100:101], v[132:133]
	v_pk_fma_f32 v[134:135], v[6:7], v[102:103], v[134:135]
	v_pk_fma_f32 v[128:129], v[16:17], v[112:113], v[128:129]
	v_pk_fma_f32 v[130:131], v[18:19], v[114:115], v[130:131]
	v_pk_fma_f32 v[132:133], v[20:21], v[116:117], v[132:133]
	v_pk_fma_f32 v[134:135], v[22:23], v[118:119], v[134:135]
	v_pk_mul_f32 v[128:129], v[128:129], v[120:121]
	v_pk_mul_f32 v[130:131], v[130:131], v[122:123]
	v_pk_mul_f32 v[132:133], v[132:133], v[124:125]
	v_pk_mul_f32 v[134:135], v[134:135], v[126:127]
	v_cvt_pk_bf16_f32 v140, v128, v129
	v_cvt_pk_bf16_f32 v141, v130, v131
	v_cvt_pk_bf16_f32 v142, v132, v133
	v_cvt_pk_bf16_f32 v143, v134, v135
	global_store_dwordx4 v158, v[140:143], s[68:69] offset:2048
	v_add_u32_e32 v158, 0x1000, v158
	s_waitcnt vmcnt(10)
; __device__ __forceinline__ unsigned cvtpk(float lo, float hi) { f32x2_t v = {lo, hi}; bf16x2_t b = __builtin_convertvector(v, bf16x2_t); return __builtin_bit_cast(unsigned, b); }
; #define LDZ(row, z) do { const bf16x8 c_ = *reinterpret_cast<const bf16x8*>(proj + (long)(row) * LDP + 4096 + c8);     \
;     _Pragma("unroll") for (int e = 0; e < 8; ++e) z[e] = __uint_as_float(((unsigned)(unsigned short)c_[e]) << 16); } while (0)
; __device__ __forceinline__ void conv_tile(const bf16* __restrict__ proj, bf16* __restrict__ cat, const float* __restrict__ cw, long row0, int ch0, int lane) {
;     ...
;   for (int i = 0; i < 8; ++i) { const long row = r0 + i;
;     if (((row + 1) & (SEQ - 1)) == 0) {
; #pragma unroll
;       for (int e = 0; e < 8; ++e) zn[e] = 0.f;
;     } else LDZ(row + 1, zn);
;     const bf16x8 gb = *reinterpret_cast<const bf16x8*>(proj + row * LDP + 3072 + c8);
;     float y[8];
; #pragma unroll
;     for (int e = 0; e < 8; ++e) y[e] = __uint_as_float(((unsigned)(unsigned short)gb[e]) << 16) * (zp[e] * w0[e] + zc[e] * w1[e] + zn[e] * w2[e]);
;     u32x4 w; w.x = cvtpk(y[0], y[1]); w.y = cvtpk(y[2], y[3]); w.z = cvtpk(y[4], y[5]); w.w = cvtpk(y[6], y[7]);
;     *(u32x4*)(cat + row * LDC + 1024 + c8) = w;
; #pragma unroll
;     for (int e = 0; e < 8; ++e) { zp[e] = zc[e]; zc[e] = zn[e]; }
;   }
	v_lshlrev_b32_e32 v96, 16, v48
	v_and_b32_e32 v97, 0xffff0000, v48
	v_lshlrev_b32_e32 v98, 16, v49
	v_and_b32_e32 v99, 0xffff0000, v49
	v_lshlrev_b32_e32 v100, 16, v50
	v_and_b32_e32 v101, 0xffff0000, v50
	v_lshlrev_b32_e32 v102, 16, v51
	v_and_b32_e32 v103, 0xffff0000, v51
	v_lshlrev_b32_e32 v120, 16, v80
	v_and_b32_e32 v121, 0xffff0000, v80
	v_lshlrev_b32_e32 v122, 16, v81
	v_and_b32_e32 v123, 0xffff0000, v81
	v_lshlrev_b32_e32 v124, 16, v82
	v_and_b32_e32 v125, 0xffff0000, v82
	v_lshlrev_b32_e32 v126, 16, v83
	v_and_b32_e32 v127, 0xffff0000, v83
	v_pk_mul_f32 v[128:129], v[8:9], v[112:113]
	v_pk_mul_f32 v[130:131], v[10:11], v[114:115]
	v_pk_mul_f32 v[132:133], v[12:13], v[116:117]
	v_pk_mul_f32 v[134:135], v[14:15], v[118:119]
	v_pk_fma_f32 v[128:129], v[0:1], v[104:105], v[128:129]
	v_pk_fma_f32 v[130:131], v[2:3], v[106:107], v[130:131]
	v_pk_fma_f32 v[132:133], v[4:5], v[108:109], v[132:133]
	v_pk_fma_f32 v[134:135], v[6:7], v[110:111], v[134:135]
	v_pk_fma_f32 v[128:129], v[16:17], v[96:97], v[128:129]
	v_pk_fma_f32 v[130:131], v[18:19], v[98:99], v[130:131]
	v_pk_fma_f32 v[132:133], v[20:21], v[100:101], v[132:133]
	v_pk_fma_f32 v[134:135], v[22:23], v[102:103], v[134:135]
	v_pk_mul_f32 v[128:129], v[128:129], v[120:121]
	v_pk_mul_f32 v[130:131], v[130:131], v[122:123]
	v_pk_mul_f32 v[132:133], v[132:133], v[124:125]
	v_pk_mul_f32 v[134:135], v[134:135], v[126:127]
	v_cvt_pk_bf16_f32 v136, v128, v129
	v_cvt_pk_bf16_f32 v137, v130, v131
	v_cvt_pk_bf16_f32 v138, v132, v133
	v_cvt_pk_bf16_f32 v139, v134, v135
	global_store_dwordx4 v158, v[136:139], s[68:69] offset:2048
	v_add_u32_e32 v158, 0x1000, v158
	s_waitcnt vmcnt(9)
	v_lshlrev_b32_e32 v104, 16, v52
	v_and_b32_e32 v105, 0xffff0000, v52
	v_lshlrev_b32_e32 v106, 16, v53
	v_and_b32_e32 v107, 0xffff0000, v53
	v_lshlrev_b32_e32 v108, 16, v54
	v_and_b32_e32 v109, 0xffff0000, v54
	v_lshlrev_b32_e32 v110, 16, v55
	v_and_b32_e32 v111, 0xffff0000, v55
	v_lshlrev_b32_e32 v120, 16, v84
	v_and_b32_e32 v121, 0xffff0000, v84
	v_lshlrev_b32_e32 v122, 16, v85
	v_and_b32_e32 v123, 0xffff0000, v85
	v_lshlrev_b32_e32 v124, 16, v86
	v_and_b32_e32 v125, 0xffff0000, v86
	v_lshlrev_b32_e32 v126, 16, v87
	v_and_b32_e32 v127, 0xffff0000, v87
	v_pk_mul_f32 v[128:129], v[8:9], v[96:97]
	v_pk_mul_f32 v[130:131], v[10:11], v[98:99]
	v_pk_mul_f32 v[132:133], v[12:13], v[100:101]
	v_pk_mul_f32 v[134:135], v[14:15], v[102:103]
	v_pk_fma_f32 v[128:129], v[0:1], v[112:113], v[128:129]
	v_pk_fma_f32 v[130:131], v[2:3], v[114:115], v[130:131]
	v_pk_fma_f32 v[132:133], v[4:5], v[116:117], v[132:133]
	v_pk_fma_f32 v[134:135], v[6:7], v[118:119], v[134:135]
	v_pk_fma_f32 v[128:129], v[16:17], v[104:105], v[128:129]
	v_pk_fma_f32 v[130:131], v[18:19], v[106:107], v[130:131]
	v_pk_fma_f32 v[132:133], v[20:21], v[108:109], v[132:133]
	v_pk_fma_f32 v[134:135], v[22:23], v[110:111], v[134:135]
	v_pk_mul_f32 v[128:129], v[128:129], v[120:121]
	v_pk_mul_f32 v[130:131], v[130:131], v[122:123]
	v_pk_mul_f32 v[132:133], v[132:133], v[124:125]
	v_pk_mul_f32 v[134:135], v[134:135], v[126:127]
	v_cvt_pk_bf16_f32 v140, v128, v129
	v_cvt_pk_bf16_f32 v141, v130, v131
	v_cvt_pk_bf16_f32 v142, v132, v133
	v_cvt_pk_bf16_f32 v143, v134, v135
	global_store_dwordx4 v158, v[140:143], s[68:69] offset:2048
	v_add_u32_e32 v158, 0x1000, v158
	s_waitcnt vmcnt(8)
	v_lshlrev_b32_e32 v112, 16, v56
	v_and_b32_e32 v113, 0xffff0000, v56
	v_lshlrev_b32_e32 v114, 16, v57
	v_and_b32_e32 v115, 0xffff0000, v57
	v_lshlrev_b32_e32 v116, 16, v58
	v_and_b32_e32 v117, 0xffff0000, v58
	v_lshlrev_b32_e32 v118, 16, v59
	v_and_b32_e32 v119, 0xffff0000, v59
	v_lshlrev_b32_e32 v120, 16, v88
	v_and_b32_e32 v121, 0xffff0000, v88
	v_lshlrev_b32_e32 v122, 16, v89
	v_and_b32_e32 v123, 0xffff0000, v89
	v_lshlrev_b32_e32 v124, 16, v90
	v_and_b32_e32 v125, 0xffff0000, v90
	v_lshlrev_b32_e32 v126, 16, v91
	v_and_b32_e32 v127, 0xffff0000, v91
	v_pk_mul_f32 v[128:129], v[8:9], v[104:105]
	v_pk_mul_f32 v[130:131], v[10:11], v[106:107]
	v_pk_mul_f32 v[132:133], v[12:13], v[108:109]
	v_pk_mul_f32 v[134:135], v[14:15], v[110:111]
	v_pk_fma_f32 v[128:129], v[0:1], v[96:97], v[128:129]
	v_pk_fma_f32 v[130:131], v[2:3], v[98:99], v[130:131]
	v_pk_fma_f32 v[132:133], v[4:5], v[100:101], v[132:133]
	v_pk_fma_f32 v[134:135], v[6:7], v[102:103], v[134:135]
	v_pk_fma_f32 v[128:129], v[16:17], v[112:113], v[128:129]
	v_pk_fma_f32 v[130:131], v[18:19], v[114:115], v[130:131]
	v_pk_fma_f32 v[132:133], v[20:21], v[116:117], v[132:133]
	v_pk_fma_f32 v[134:135], v[22:23], v[118:119], v[134:135]
	v_pk_mul_f32 v[128:129], v[128:129], v[120:121]
	v_pk_mul_f32 v[130:131], v[130:131], v[122:123]
	v_pk_mul_f32 v[132:133], v[132:133], v[124:125]
	v_pk_mul_f32 v[134:135], v[134:135], v[126:127]
	v_cvt_pk_bf16_f32 v136, v128, v129
	v_cvt_pk_bf16_f32 v137, v130, v131
	v_cvt_pk_bf16_f32 v138, v132, v133
	v_cvt_pk_bf16_f32 v139, v134, v135
	global_store_dwordx4 v158, v[136:139], s[68:69] offset:2048
	v_add_u32_e32 v158, 0x1000, v158
	s_waitcnt vmcnt(7)
	v_lshlrev_b32_e32 v96, 16, v60
	v_and_b32_e32 v97, 0xffff0000, v60
	v_lshlrev_b32_e32 v98, 16, v61
	v_and_b32_e32 v99, 0xffff0000, v61
	v_lshlrev_b32_e32 v100, 16, v62
	v_and_b32_e32 v101, 0xffff0000, v62
	v_lshlrev_b32_e32 v102, 16, v63
	v_and_b32_e32 v103, 0xffff0000, v63
	v_lshlrev_b32_e32 v120, 16, v92
	v_and_b32_e32 v121, 0xffff0000, v92
	v_lshlrev_b32_e32 v122, 16, v93
	v_and_b32_e32 v123, 0xffff0000, v93
	v_lshlrev_b32_e32 v124, 16, v94
	v_and_b32_e32 v125, 0xffff0000, v94
	v_lshlrev_b32_e32 v126, 16, v95
	v_and_b32_e32 v127, 0xffff0000, v95
	v_pk_mul_f32 v[128:129], v[8:9], v[112:113]
	v_pk_mul_f32 v[130:131], v[10:11], v[114:115]
	v_pk_mul_f32 v[132:133], v[12:13], v[116:117]
	v_pk_mul_f32 v[134:135], v[14:15], v[118:119]
	v_pk_fma_f32 v[128:129], v[0:1], v[104:105], v[128:129]
	v_pk_fma_f32 v[130:131], v[2:3], v[106:107], v[130:131]
	v_pk_fma_f32 v[132:133], v[4:5], v[108:109], v[132:133]
	v_pk_fma_f32 v[134:135], v[6:7], v[110:111], v[134:135]
	v_pk_fma_f32 v[128:129], v[16:17], v[96:97], v[128:129]
	v_pk_fma_f32 v[130:131], v[18:19], v[98:99], v[130:131]
	v_pk_fma_f32 v[132:133], v[20:21], v[100:101], v[132:133]
	v_pk_fma_f32 v[134:135], v[22:23], v[102:103], v[134:135]
	v_pk_mul_f32 v[128:129], v[128:129], v[120:121]
	v_pk_mul_f32 v[130:131], v[130:131], v[122:123]
	v_pk_mul_f32 v[132:133], v[132:133], v[124:125]
	v_pk_mul_f32 v[134:135], v[134:135], v[126:127]
	v_cvt_pk_bf16_f32 v140, v128, v129
	v_cvt_pk_bf16_f32 v141, v130, v131
	v_cvt_pk_bf16_f32 v142, v132, v133
	v_cvt_pk_bf16_f32 v143, v134, v135
	global_store_dwordx4 v158, v[140:143], s[68:69] offset:2048
	s_mov_b64 s[20:21], 0
; __device__ __forceinline__ int crow(int r, int hi) { return (r & 3) + 8 * (r >> 2) + 4 * hi; }
; __device__ __forceinline__ void conv_tile(const bf16* __restrict__ proj, bf16* __restrict__ cat, const float* __restrict__ cw, long row0, int ch0, int lane) {
;     ...
;     *(u32x4*)(cat + row * LDC + 1024 + c8) = w;
; #pragma unroll
;     for (int e = 0; e < 8; ++e) { zp[e] = zc[e]; zc[e] = zn[e]; }
;   }
; __device__ __forceinline__ void attn_unit(const bf16* __restrict__ proj, bf16* __restrict__ cat, int b, int h, int qb, float lam, float oscale, const float* __restrict__ subln, const float* __restrict__ cw, char* lds) {
;     ...
;   if (mp == 0) {
;     float g[4];
; #pragma unroll
;     for (int d0 = 0; d0 < 4; ++d0) g[d0] = subln[d0 * 32 + r32] * oscale;
;     bf16* stg = (bf16*)(lds + OFF_STG) + rg * (32 * 128);
; #pragma unroll
;     for (int r = 0; r < 16; ++r) { float s = 0.f;
; #pragma unroll
;       for (int d0 = 0; d0 < 4; ++d0) { const float v = o[d0][r] * rli[r] - X[(d0 * 16 + r) * 64 + lane]; o[d0][r] = v; s += v * v; }
;       s += __shfl_xor(s, 1); s += __shfl_xor(s, 2); s += __shfl_xor(s, 4); s += __shfl_xor(s, 8); s += __shfl_xor(s, 16);
;       const float rs = __builtin_amdgcn_rsqf(s * (1.f / 128.f) + 1e-6f); const int orow = crow(r, hi);
.LBB0_248:
	s_and_b64 vcc, exec, s[20:21]
	s_cbranch_vccz .LBB0_207
	v_lshlrev_b32_e32 v67, 2, v174
	global_load_dword v64, v67, s[40:41]
	global_load_dword v65, v67, s[40:41] offset:128
	global_load_dword v66, v67, s[40:41] offset:256
	ds_read2st64_b32 v[70:71], v136 offset1:1
	ds_read2st64_b32 v[72:73], v136 offset0:16 offset1:17
	ds_read2st64_b32 v[74:75], v136 offset0:32 offset1:33
	ds_read2st64_b32 v[76:77], v136 offset0:48 offset1:49
	global_load_dword v67, v67, s[40:41] offset:384
	s_lshl_b32 s20, s29, 13
	s_add_i32 s20, s20, 0
	s_add_i32 s20, s20, 0x10000
	v_lshlrev_b32_e32 v68, 10, v179
	v_lshlrev_b32_e32 v69, 1, v174
	s_waitcnt lgkmcnt(0)
	v_fma_f32 v48, v48, v150, -v72
	v_add3_u32 v68, s20, v68, v69
	v_fma_f32 v0, v0, v150, -v70
	v_mul_f32_e32 v69, v48, v48
	v_fmac_f32_e32 v69, v0, v0
	s_waitcnt lgkmcnt(0)
	v_fma_f32 v32, v32, v150, -v74
	v_fmac_f32_e32 v69, v32, v32
	s_waitcnt lgkmcnt(0)
	v_fma_f32 v16, v16, v150, -v76
	v_fmac_f32_e32 v69, v16, v16
	v_fma_f32 v17, v17, v149, -v77
	s_lshl_b64 s[24:25], s[44:45], 12
	s_add_u32 s21, s68, s24
	s_addc_u32 s25, s69, s25
	s_waitcnt lgkmcnt(0)
	s_nop 1
	v_add_f32_dpp v69, v69, v69 quad_perm:[1,0,3,2] row_mask:0xf bank_mask:0xf
	s_lshl_b32 s24, s28, 1
	s_add_u32 s24, s21, s24
	s_addc_u32 s25, s25, 0
	s_waitcnt lgkmcnt(0)
	s_nop 1
	v_add_f32_dpp v69, v69, v69 quad_perm:[2,3,0,1] row_mask:0xf bank_mask:0xf
	s_waitcnt lgkmcnt(0)
	s_nop 1
	v_add_f32_dpp v69, v69, v69 row_half_mirror row_mask:0xf bank_mask:0xf
	s_waitcnt lgkmcnt(0)
	s_nop 1
	v_add_f32_dpp v69, v69, v69 row_mirror row_mask:0xf bank_mask:0xf
	ds_bpermute_b32 v70, v208, v69
	s_waitcnt lgkmcnt(0)
	v_add_f32_e32 v69, v69, v70
	v_fmamk_f32 v69, v69, 0x3c000000, v194
	v_rsq_f32_e32 v69, v69
	s_waitcnt vmcnt(3)
	v_mul_f32_e32 v64, v175, v64
	v_mul_f32_e32 v0, v0, v69
	v_mul_f32_e32 v0, v64, v0
	v_cvt_pk_bf16_f32 v0, v0, s0
	s_waitcnt vmcnt(2)
	v_mul_f32_e32 v65, v175, v65
	ds_write_b16 v68, v0
	v_mul_f32_e32 v0, v48, v69
	v_mul_f32_e32 v0, v65, v0
	v_cvt_pk_bf16_f32 v0, v0, s0
	s_waitcnt vmcnt(1)
	v_mul_f32_e32 v66, v175, v66
	ds_write_b16 v68, v0 offset:64
	v_mul_f32_e32 v0, v32, v69
	v_mul_f32_e32 v0, v66, v0
	v_cvt_pk_bf16_f32 v0, v0, s0
	s_waitcnt vmcnt(0)
	v_mul_f32_e32 v67, v175, v67
	ds_write_b16 v68, v0 offset:128
	v_mul_f32_e32 v0, v16, v69
	v_mul_f32_e32 v0, v67, v0
	v_cvt_pk_bf16_f32 v0, v0, s0
	ds_write_b16 v68, v0 offset:192
	v_fma_f32 v0, v1, v149, -v71
	v_fma_f32 v1, v49, v149, -v73
	v_mul_f32_e32 v16, v1, v1
	v_fmac_f32_e32 v16, v0, v0
	v_fma_f32 v32, v33, v149, -v75
	v_fmac_f32_e32 v16, v32, v32
	v_fmac_f32_e32 v16, v17, v17
	ds_read2st64_b32 v[48:49], v136 offset0:50 offset1:51
	s_waitcnt lgkmcnt(0)
	s_nop 1
	v_add_f32_dpp v16, v16, v16 quad_perm:[1,0,3,2] row_mask:0xf bank_mask:0xf
	s_waitcnt lgkmcnt(0)
	v_fma_f32 v18, v18, v148, -v48
	s_waitcnt lgkmcnt(0)
	s_nop 1
	v_add_f32_dpp v16, v16, v16 quad_perm:[2,3,0,1] row_mask:0xf bank_mask:0xf
	s_waitcnt lgkmcnt(0)
	s_nop 1
	v_add_f32_dpp v16, v16, v16 row_half_mirror row_mask:0xf bank_mask:0xf
	s_waitcnt lgkmcnt(0)
	s_nop 1
	v_add_f32_dpp v16, v16, v16 row_mirror row_mask:0xf bank_mask:0xf
	ds_bpermute_b32 v33, v208, v16
	s_waitcnt lgkmcnt(0)
	v_add_f32_e32 v16, v16, v33
	v_fmamk_f32 v16, v16, 0x3c000000, v194
	v_rsq_f32_e32 v16, v16
	s_nop 0
	v_mul_f32_e32 v0, v0, v16
	v_mul_f32_e32 v0, v64, v0
	v_cvt_pk_bf16_f32 v0, v0, s0
	ds_write_b16 v68, v0 offset:256
	v_mul_f32_e32 v0, v1, v16
	v_mul_f32_e32 v0, v65, v0
	v_cvt_pk_bf16_f32 v0, v0, s0
	ds_write_b16 v68, v0 offset:320
	v_mul_f32_e32 v0, v32, v16
	v_mul_f32_e32 v0, v66, v0
	v_cvt_pk_bf16_f32 v0, v0, s0
	ds_write_b16 v68, v0 offset:384
	v_mul_f32_e32 v0, v17, v16
	v_mul_f32_e32 v0, v67, v0
	v_cvt_pk_bf16_f32 v0, v0, s0
	ds_write_b16 v68, v0 offset:448
	ds_read2st64_b32 v[0:1], v136 offset0:2 offset1:3
	ds_read2st64_b32 v[16:17], v136 offset0:18 offset1:19
	ds_read2st64_b32 v[32:33], v136 offset0:34 offset1:35
	s_waitcnt lgkmcnt(0)
	v_fma_f32 v0, v2, v148, -v0
	s_waitcnt lgkmcnt(0)
	v_fma_f32 v2, v50, v148, -v16
	v_mul_f32_e32 v16, v2, v2
	v_fmac_f32_e32 v16, v0, v0
	s_waitcnt lgkmcnt(0)
	v_fma_f32 v32, v34, v148, -v32
	v_fmac_f32_e32 v16, v32, v32
	v_fmac_f32_e32 v16, v18, v18
	s_waitcnt lgkmcnt(0)
	s_nop 1
	v_add_f32_dpp v16, v16, v16 quad_perm:[1,0,3,2] row_mask:0xf bank_mask:0xf
	s_waitcnt lgkmcnt(0)
	s_nop 1
	v_add_f32_dpp v16, v16, v16 quad_perm:[2,3,0,1] row_mask:0xf bank_mask:0xf
	s_waitcnt lgkmcnt(0)
	s_nop 1
	v_add_f32_dpp v16, v16, v16 row_half_mirror row_mask:0xf bank_mask:0xf
	s_waitcnt lgkmcnt(0)
	s_nop 1
	v_add_f32_dpp v16, v16, v16 row_mirror row_mask:0xf bank_mask:0xf
	ds_bpermute_b32 v34, v208, v16
	s_waitcnt lgkmcnt(0)
	v_add_f32_e32 v16, v16, v34
	v_fmamk_f32 v16, v16, 0x3c000000, v194
	v_rsq_f32_e32 v16, v16
	s_nop 0
	v_mul_f32_e32 v0, v0, v16
	v_mul_f32_e32 v0, v64, v0
	v_cvt_pk_bf16_f32 v0, v0, s0
	ds_write_b16 v68, v0 offset:512
	v_mul_f32_e32 v0, v2, v16
	v_mul_f32_e32 v0, v65, v0
	v_cvt_pk_bf16_f32 v0, v0, s0
	ds_write_b16 v68, v0 offset:576
	v_mul_f32_e32 v0, v32, v16
	v_mul_f32_e32 v0, v66, v0
	v_cvt_pk_bf16_f32 v0, v0, s0
	ds_write_b16 v68, v0 offset:640
	v_mul_f32_e32 v0, v18, v16
	v_mul_f32_e32 v0, v67, v0
	v_cvt_pk_bf16_f32 v0, v0, s0
	ds_write_b16 v68, v0 offset:704
	v_fma_f32 v0, v3, v147, -v1
	v_fma_f32 v1, v51, v147, -v17
	v_mul_f32_e32 v2, v1, v1
	v_fmac_f32_e32 v2, v0, v0
	v_fma_f32 v3, v35, v147, -v33
	v_fmac_f32_e32 v2, v3, v3
	v_fma_f32 v16, v19, v147, -v49
	v_fmac_f32_e32 v2, v16, v16
	ds_read2st64_b32 v[18:19], v136 offset0:52 offset1:53
	s_waitcnt lgkmcnt(0)
	s_nop 1
	v_add_f32_dpp v2, v2, v2 quad_perm:[1,0,3,2] row_mask:0xf bank_mask:0xf
	s_waitcnt lgkmcnt(0)
; __device__ __forceinline__ int crow(int r, int hi) { return (r & 3) + 8 * (r >> 2) + 4 * hi; }
; __device__ __forceinline__ void attn_unit(const bf16* __restrict__ proj, bf16* __restrict__ cat, int b, int h, int qb, float lam, float oscale, const float* __restrict__ subln, const float* __restrict__ cw, char* lds) {
;     ...
;     for (int r = 0; r < 16; ++r) { float s = 0.f;
; #pragma unroll
;       for (int d0 = 0; d0 < 4; ++d0) { const float v = o[d0][r] * rli[r] - X[(d0 * 16 + r) * 64 + lane]; o[d0][r] = v; s += v * v; }
;       s += __shfl_xor(s, 1); s += __shfl_xor(s, 2); s += __shfl_xor(s, 4); s += __shfl_xor(s, 8); s += __shfl_xor(s, 16);
;       const float rs = __builtin_amdgcn_rsqf(s * (1.f / 128.f) + 1e-6f); const int orow = crow(r, hi);
; #pragma unroll
;       for (int d0 = 0; d0 < 4; ++d0) stg[orow * 128 + d0 * 32 + r32] = __float2bfloat16(o[d0][r] * rs * g[d0]); }
	v_fma_f32 v18, v20, v146, -v18
	s_waitcnt lgkmcnt(0)
	s_nop 1
	v_add_f32_dpp v2, v2, v2 quad_perm:[2,3,0,1] row_mask:0xf bank_mask:0xf
	s_waitcnt lgkmcnt(0)
	s_nop 1
	v_add_f32_dpp v2, v2, v2 row_half_mirror row_mask:0xf bank_mask:0xf
	s_waitcnt lgkmcnt(0)
	s_nop 1
	v_add_f32_dpp v2, v2, v2 row_mirror row_mask:0xf bank_mask:0xf
	ds_bpermute_b32 v17, v208, v2
	s_waitcnt lgkmcnt(0)
	v_add_f32_e32 v2, v2, v17
	v_fmamk_f32 v2, v2, 0x3c000000, v194
	v_rsq_f32_e32 v2, v2
	s_nop 0
	v_mul_f32_e32 v0, v0, v2
	v_mul_f32_e32 v0, v64, v0
	v_cvt_pk_bf16_f32 v0, v0, s0
	ds_write_b16 v68, v0 offset:768
	v_mul_f32_e32 v0, v1, v2
	v_mul_f32_e32 v0, v65, v0
	v_cvt_pk_bf16_f32 v0, v0, s0
	ds_write_b16 v68, v0 offset:832
	v_mul_f32_e32 v0, v3, v2
	v_mul_f32_e32 v0, v66, v0
	v_cvt_pk_bf16_f32 v0, v0, s0
	ds_write_b16 v68, v0 offset:896
	v_mul_f32_e32 v0, v16, v2
	v_mul_f32_e32 v0, v67, v0
	v_cvt_pk_bf16_f32 v0, v0, s0
	ds_write_b16 v68, v0 offset:960
	ds_read2st64_b32 v[0:1], v136 offset0:4 offset1:5
	ds_read2st64_b32 v[2:3], v136 offset0:20 offset1:21
	ds_read2st64_b32 v[16:17], v136 offset0:36 offset1:37
	s_waitcnt lgkmcnt(0)
	v_fma_f32 v0, v4, v146, -v0
	s_waitcnt lgkmcnt(0)
	v_fma_f32 v2, v52, v146, -v2
	v_mul_f32_e32 v4, v2, v2
	v_fmac_f32_e32 v4, v0, v0
	s_waitcnt lgkmcnt(0)
	v_fma_f32 v16, v36, v146, -v16
	v_fmac_f32_e32 v4, v16, v16
	v_fmac_f32_e32 v4, v18, v18
	s_waitcnt lgkmcnt(0)
	s_nop 1
	v_add_f32_dpp v4, v4, v4 quad_perm:[1,0,3,2] row_mask:0xf bank_mask:0xf
	s_waitcnt lgkmcnt(0)
	s_nop 1
	v_add_f32_dpp v4, v4, v4 quad_perm:[2,3,0,1] row_mask:0xf bank_mask:0xf
	s_waitcnt lgkmcnt(0)
	s_nop 1
	v_add_f32_dpp v4, v4, v4 row_half_mirror row_mask:0xf bank_mask:0xf
	s_waitcnt lgkmcnt(0)
	s_nop 1
	v_add_f32_dpp v4, v4, v4 row_mirror row_mask:0xf bank_mask:0xf
	ds_bpermute_b32 v20, v208, v4
	s_waitcnt lgkmcnt(0)
	v_add_f32_e32 v4, v4, v20
	v_fmamk_f32 v4, v4, 0x3c000000, v194
	v_rsq_f32_e32 v4, v4
	s_nop 0
	v_mul_f32_e32 v0, v0, v4
	v_mul_f32_e32 v0, v64, v0
	v_cvt_pk_bf16_f32 v0, v0, s0
	ds_write_b16 v68, v0 offset:2048
	v_mul_f32_e32 v0, v2, v4
	v_mul_f32_e32 v0, v65, v0
	v_cvt_pk_bf16_f32 v0, v0, s0
	ds_write_b16 v68, v0 offset:2112
	v_mul_f32_e32 v0, v16, v4
	v_mul_f32_e32 v0, v66, v0
	v_cvt_pk_bf16_f32 v0, v0, s0
	ds_write_b16 v68, v0 offset:2176
	v_mul_f32_e32 v0, v18, v4
	v_mul_f32_e32 v0, v67, v0
	v_cvt_pk_bf16_f32 v0, v0, s0
	ds_write_b16 v68, v0 offset:2240
	v_fma_f32 v0, v5, v145, -v1
	v_fma_f32 v1, v53, v145, -v3
	v_mul_f32_e32 v2, v1, v1
	v_fmac_f32_e32 v2, v0, v0
	v_fma_f32 v3, v37, v145, -v17
	v_fmac_f32_e32 v2, v3, v3
	v_fma_f32 v4, v21, v145, -v19
	v_fmac_f32_e32 v2, v4, v4
	ds_read2st64_b32 v[16:17], v136 offset0:54 offset1:55
	s_waitcnt lgkmcnt(0)
	s_nop 1
	v_add_f32_dpp v2, v2, v2 quad_perm:[1,0,3,2] row_mask:0xf bank_mask:0xf
	s_waitcnt lgkmcnt(0)
	v_fma_f32 v16, v22, v144, -v16
	s_waitcnt lgkmcnt(0)
	s_nop 1
	v_add_f32_dpp v2, v2, v2 quad_perm:[2,3,0,1] row_mask:0xf bank_mask:0xf
	s_waitcnt lgkmcnt(0)
	s_nop 1
	v_add_f32_dpp v2, v2, v2 row_half_mirror row_mask:0xf bank_mask:0xf
	s_waitcnt lgkmcnt(0)
	s_nop 1
	v_add_f32_dpp v2, v2, v2 row_mirror row_mask:0xf bank_mask:0xf
	ds_bpermute_b32 v5, v208, v2
	s_waitcnt lgkmcnt(0)
	v_add_f32_e32 v2, v2, v5
	v_fmamk_f32 v2, v2, 0x3c000000, v194
	v_rsq_f32_e32 v2, v2
	s_nop 0
	v_mul_f32_e32 v0, v0, v2
	v_mul_f32_e32 v0, v64, v0
	v_cvt_pk_bf16_f32 v0, v0, s0
	ds_write_b16 v68, v0 offset:2304
	v_mul_f32_e32 v0, v1, v2
	v_mul_f32_e32 v0, v65, v0
	v_cvt_pk_bf16_f32 v0, v0, s0
	ds_write_b16 v68, v0 offset:2368
	v_mul_f32_e32 v0, v3, v2
	v_mul_f32_e32 v0, v66, v0
	v_cvt_pk_bf16_f32 v0, v0, s0
	ds_write_b16 v68, v0 offset:2432
	v_mul_f32_e32 v0, v4, v2
	v_mul_f32_e32 v0, v67, v0
	v_cvt_pk_bf16_f32 v0, v0, s0
	ds_write_b16 v68, v0 offset:2496
	ds_read2st64_b32 v[0:1], v136 offset0:6 offset1:7
	ds_read2st64_b32 v[2:3], v136 offset0:22 offset1:23
	ds_read2st64_b32 v[4:5], v136 offset0:38 offset1:39
	s_waitcnt lgkmcnt(0)
	v_fma_f32 v0, v6, v144, -v0
	s_waitcnt lgkmcnt(0)
	v_fma_f32 v2, v54, v144, -v2
	v_mul_f32_e32 v6, v2, v2
	v_fmac_f32_e32 v6, v0, v0
	s_waitcnt lgkmcnt(0)
	v_fma_f32 v4, v38, v144, -v4
	v_fmac_f32_e32 v6, v4, v4
	v_fmac_f32_e32 v6, v16, v16
	s_waitcnt lgkmcnt(0)
	s_nop 1
	v_add_f32_dpp v6, v6, v6 quad_perm:[1,0,3,2] row_mask:0xf bank_mask:0xf
	s_waitcnt lgkmcnt(0)
	s_nop 1
	v_add_f32_dpp v6, v6, v6 quad_perm:[2,3,0,1] row_mask:0xf bank_mask:0xf
	s_waitcnt lgkmcnt(0)
	s_nop 1
	v_add_f32_dpp v6, v6, v6 row_half_mirror row_mask:0xf bank_mask:0xf
	s_waitcnt lgkmcnt(0)
	s_nop 1
	v_add_f32_dpp v6, v6, v6 row_mirror row_mask:0xf bank_mask:0xf
	ds_bpermute_b32 v18, v208, v6
	s_waitcnt lgkmcnt(0)
	v_add_f32_e32 v6, v6, v18
	v_fmamk_f32 v6, v6, 0x3c000000, v194
	v_rsq_f32_e32 v6, v6
	s_nop 0
	v_mul_f32_e32 v0, v0, v6
	v_mul_f32_e32 v0, v64, v0
	v_cvt_pk_bf16_f32 v0, v0, s0
	ds_write_b16 v68, v0 offset:2560
	v_mul_f32_e32 v0, v2, v6
	v_mul_f32_e32 v0, v65, v0
	v_cvt_pk_bf16_f32 v0, v0, s0
	ds_write_b16 v68, v0 offset:2624
	v_mul_f32_e32 v0, v4, v6
	v_mul_f32_e32 v0, v66, v0
	v_cvt_pk_bf16_f32 v0, v0, s0
	ds_write_b16 v68, v0 offset:2688
	v_mul_f32_e32 v0, v16, v6
	v_mul_f32_e32 v0, v67, v0
	v_cvt_pk_bf16_f32 v0, v0, s0
	ds_write_b16 v68, v0 offset:2752
	v_fma_f32 v0, v7, v143, -v1
	v_fma_f32 v1, v55, v143, -v3
	v_mul_f32_e32 v2, v1, v1
	v_fmac_f32_e32 v2, v0, v0
	v_fma_f32 v3, v39, v143, -v5
	v_fmac_f32_e32 v2, v3, v3
	v_fma_f32 v4, v23, v143, -v17
	v_fmac_f32_e32 v2, v4, v4
	ds_read2st64_b32 v[6:7], v136 offset0:56 offset1:57
	s_waitcnt lgkmcnt(0)
	s_nop 1
	v_add_f32_dpp v2, v2, v2 quad_perm:[1,0,3,2] row_mask:0xf bank_mask:0xf
	s_waitcnt lgkmcnt(0)
	v_fma_f32 v6, v24, v142, -v6
	s_waitcnt lgkmcnt(0)
; __device__ __forceinline__ int crow(int r, int hi) { return (r & 3) + 8 * (r >> 2) + 4 * hi; }
; __device__ __forceinline__ void attn_unit(const bf16* __restrict__ proj, bf16* __restrict__ cat, int b, int h, int qb, float lam, float oscale, const float* __restrict__ subln, const float* __restrict__ cw, char* lds) {
;     ...
;     for (int r = 0; r < 16; ++r) { float s = 0.f;
; #pragma unroll
;       for (int d0 = 0; d0 < 4; ++d0) { const float v = o[d0][r] * rli[r] - X[(d0 * 16 + r) * 64 + lane]; o[d0][r] = v; s += v * v; }
;       s += __shfl_xor(s, 1); s += __shfl_xor(s, 2); s += __shfl_xor(s, 4); s += __shfl_xor(s, 8); s += __shfl_xor(s, 16);
;       const float rs = __builtin_amdgcn_rsqf(s * (1.f / 128.f) + 1e-6f); const int orow = crow(r, hi);
; #pragma unroll
;       for (int d0 = 0; d0 < 4; ++d0) stg[orow * 128 + d0 * 32 + r32] = __float2bfloat16(o[d0][r] * rs * g[d0]); }
	s_nop 1
	v_add_f32_dpp v2, v2, v2 quad_perm:[2,3,0,1] row_mask:0xf bank_mask:0xf
	s_waitcnt lgkmcnt(0)
	s_nop 1
	v_add_f32_dpp v2, v2, v2 row_half_mirror row_mask:0xf bank_mask:0xf
	s_waitcnt lgkmcnt(0)
	s_nop 1
	v_add_f32_dpp v2, v2, v2 row_mirror row_mask:0xf bank_mask:0xf
	ds_bpermute_b32 v5, v208, v2
	s_waitcnt lgkmcnt(0)
	v_add_f32_e32 v2, v2, v5
	v_fmamk_f32 v2, v2, 0x3c000000, v194
	v_rsq_f32_e32 v2, v2
	s_nop 0
	v_mul_f32_e32 v0, v0, v2
	v_mul_f32_e32 v0, v64, v0
	v_cvt_pk_bf16_f32 v0, v0, s0
	ds_write_b16 v68, v0 offset:2816
	v_mul_f32_e32 v0, v1, v2
	v_mul_f32_e32 v0, v65, v0
	v_cvt_pk_bf16_f32 v0, v0, s0
	ds_write_b16 v68, v0 offset:2880
	v_mul_f32_e32 v0, v3, v2
	v_mul_f32_e32 v0, v66, v0
	v_cvt_pk_bf16_f32 v0, v0, s0
	ds_write_b16 v68, v0 offset:2944
	v_mul_f32_e32 v0, v4, v2
	v_mul_f32_e32 v0, v67, v0
	v_cvt_pk_bf16_f32 v0, v0, s0
	ds_write_b16 v68, v0 offset:3008
	ds_read2st64_b32 v[0:1], v136 offset0:8 offset1:9
	ds_read2st64_b32 v[2:3], v136 offset0:24 offset1:25
	ds_read2st64_b32 v[4:5], v136 offset0:40 offset1:41
	s_waitcnt lgkmcnt(0)
	v_fma_f32 v0, v8, v142, -v0
	s_waitcnt lgkmcnt(0)
	v_fma_f32 v2, v56, v142, -v2
	v_mul_f32_e32 v8, v2, v2
	v_fmac_f32_e32 v8, v0, v0
	s_waitcnt lgkmcnt(0)
	v_fma_f32 v4, v40, v142, -v4
	v_fmac_f32_e32 v8, v4, v4
	v_fmac_f32_e32 v8, v6, v6
	s_waitcnt lgkmcnt(0)
	s_nop 1
	v_add_f32_dpp v8, v8, v8 quad_perm:[1,0,3,2] row_mask:0xf bank_mask:0xf
	s_waitcnt lgkmcnt(0)
	s_nop 1
	v_add_f32_dpp v8, v8, v8 quad_perm:[2,3,0,1] row_mask:0xf bank_mask:0xf
	s_waitcnt lgkmcnt(0)
	s_nop 1
	v_add_f32_dpp v8, v8, v8 row_half_mirror row_mask:0xf bank_mask:0xf
	s_waitcnt lgkmcnt(0)
	s_nop 1
	v_add_f32_dpp v8, v8, v8 row_mirror row_mask:0xf bank_mask:0xf
	ds_bpermute_b32 v16, v208, v8
	s_waitcnt lgkmcnt(0)
	v_add_f32_e32 v8, v8, v16
	v_fmamk_f32 v8, v8, 0x3c000000, v194
	v_rsq_f32_e32 v8, v8
	s_nop 0
	v_mul_f32_e32 v0, v0, v8
	v_mul_f32_e32 v0, v64, v0
	v_cvt_pk_bf16_f32 v0, v0, s0
	ds_write_b16 v68, v0 offset:4096
	v_mul_f32_e32 v0, v2, v8
	v_mul_f32_e32 v0, v65, v0
	v_cvt_pk_bf16_f32 v0, v0, s0
	ds_write_b16 v68, v0 offset:4160
	v_mul_f32_e32 v0, v4, v8
	v_mul_f32_e32 v0, v66, v0
	v_cvt_pk_bf16_f32 v0, v0, s0
	ds_write_b16 v68, v0 offset:4224
	v_mul_f32_e32 v0, v6, v8
	v_mul_f32_e32 v0, v67, v0
	v_cvt_pk_bf16_f32 v0, v0, s0
	ds_write_b16 v68, v0 offset:4288
	v_fma_f32 v0, v9, v141, -v1
	v_fma_f32 v1, v57, v141, -v3
	v_mul_f32_e32 v2, v1, v1
	v_fmac_f32_e32 v2, v0, v0
	v_fma_f32 v3, v41, v141, -v5
	v_fmac_f32_e32 v2, v3, v3
	v_fma_f32 v4, v25, v141, -v7
	v_fmac_f32_e32 v2, v4, v4
	ds_read2st64_b32 v[6:7], v136 offset0:58 offset1:59
	s_waitcnt lgkmcnt(0)
	s_nop 1
	v_add_f32_dpp v2, v2, v2 quad_perm:[1,0,3,2] row_mask:0xf bank_mask:0xf
	s_waitcnt lgkmcnt(0)
	v_fma_f32 v6, v26, v140, -v6
	s_waitcnt lgkmcnt(0)
	s_nop 1
	v_add_f32_dpp v2, v2, v2 quad_perm:[2,3,0,1] row_mask:0xf bank_mask:0xf
	s_waitcnt lgkmcnt(0)
	s_nop 1
	v_add_f32_dpp v2, v2, v2 row_half_mirror row_mask:0xf bank_mask:0xf
	s_waitcnt lgkmcnt(0)
	s_nop 1
	v_add_f32_dpp v2, v2, v2 row_mirror row_mask:0xf bank_mask:0xf
	ds_bpermute_b32 v5, v208, v2
	s_waitcnt lgkmcnt(0)
	v_add_f32_e32 v2, v2, v5
	v_fmamk_f32 v2, v2, 0x3c000000, v194
	v_rsq_f32_e32 v2, v2
	s_nop 0
	v_mul_f32_e32 v0, v0, v2
	v_mul_f32_e32 v0, v64, v0
	v_cvt_pk_bf16_f32 v0, v0, s0
	ds_write_b16 v68, v0 offset:4352
	v_mul_f32_e32 v0, v1, v2
	v_mul_f32_e32 v0, v65, v0
	v_cvt_pk_bf16_f32 v0, v0, s0
	ds_write_b16 v68, v0 offset:4416
	v_mul_f32_e32 v0, v3, v2
	v_mul_f32_e32 v0, v66, v0
	v_cvt_pk_bf16_f32 v0, v0, s0
	ds_write_b16 v68, v0 offset:4480
	v_mul_f32_e32 v0, v4, v2
	v_mul_f32_e32 v0, v67, v0
	v_cvt_pk_bf16_f32 v0, v0, s0
	ds_write_b16 v68, v0 offset:4544
	ds_read2st64_b32 v[0:1], v136 offset0:10 offset1:11
	ds_read2st64_b32 v[2:3], v136 offset0:26 offset1:27
	ds_read2st64_b32 v[4:5], v136 offset0:42 offset1:43
	s_waitcnt lgkmcnt(0)
	v_fma_f32 v0, v10, v140, -v0
	s_waitcnt lgkmcnt(0)
	v_fma_f32 v2, v58, v140, -v2
	v_mul_f32_e32 v8, v2, v2
	v_fmac_f32_e32 v8, v0, v0
	s_waitcnt lgkmcnt(0)
	v_fma_f32 v4, v42, v140, -v4
	v_fmac_f32_e32 v8, v4, v4
	v_fmac_f32_e32 v8, v6, v6
	s_waitcnt lgkmcnt(0)
	s_nop 1
	v_add_f32_dpp v8, v8, v8 quad_perm:[1,0,3,2] row_mask:0xf bank_mask:0xf
	s_waitcnt lgkmcnt(0)
	s_nop 1
	v_add_f32_dpp v8, v8, v8 quad_perm:[2,3,0,1] row_mask:0xf bank_mask:0xf
	s_waitcnt lgkmcnt(0)
	s_nop 1
	v_add_f32_dpp v8, v8, v8 row_half_mirror row_mask:0xf bank_mask:0xf
	s_waitcnt lgkmcnt(0)
	s_nop 1
	v_add_f32_dpp v8, v8, v8 row_mirror row_mask:0xf bank_mask:0xf
	ds_bpermute_b32 v9, v208, v8
	s_waitcnt lgkmcnt(0)
	v_add_f32_e32 v8, v8, v9
	v_fmamk_f32 v8, v8, 0x3c000000, v194
	v_rsq_f32_e32 v8, v8
	s_nop 0
	v_mul_f32_e32 v0, v0, v8
	v_mul_f32_e32 v0, v64, v0
	v_cvt_pk_bf16_f32 v0, v0, s0
	ds_write_b16 v68, v0 offset:4608
	v_mul_f32_e32 v0, v2, v8
	v_mul_f32_e32 v0, v65, v0
	v_cvt_pk_bf16_f32 v0, v0, s0
	ds_write_b16 v68, v0 offset:4672
	v_mul_f32_e32 v0, v4, v8
	v_mul_f32_e32 v0, v66, v0
	v_cvt_pk_bf16_f32 v0, v0, s0
	ds_write_b16 v68, v0 offset:4736
	v_mul_f32_e32 v0, v6, v8
	v_mul_f32_e32 v0, v67, v0
	v_cvt_pk_bf16_f32 v0, v0, s0
	ds_write_b16 v68, v0 offset:4800
	v_fma_f32 v0, v11, v139, -v1
	v_fma_f32 v1, v59, v139, -v3
	v_mul_f32_e32 v2, v1, v1
	v_fmac_f32_e32 v2, v0, v0
	v_fma_f32 v3, v43, v139, -v5
	v_fmac_f32_e32 v2, v3, v3
	v_fma_f32 v4, v27, v139, -v7
	v_fmac_f32_e32 v2, v4, v4
	ds_read2st64_b32 v[6:7], v136 offset0:60 offset1:61
	s_waitcnt lgkmcnt(0)
	s_nop 1
	v_add_f32_dpp v2, v2, v2 quad_perm:[1,0,3,2] row_mask:0xf bank_mask:0xf
	s_waitcnt lgkmcnt(0)
	v_fma_f32 v6, v28, v138, -v6
	s_waitcnt lgkmcnt(0)
	s_nop 1
	v_add_f32_dpp v2, v2, v2 quad_perm:[2,3,0,1] row_mask:0xf bank_mask:0xf
	s_waitcnt lgkmcnt(0)
; __device__ __forceinline__ int crow(int r, int hi) { return (r & 3) + 8 * (r >> 2) + 4 * hi; }
; __device__ __forceinline__ void attn_unit(const bf16* __restrict__ proj, bf16* __restrict__ cat, int b, int h, int qb, float lam, float oscale, const float* __restrict__ subln, const float* __restrict__ cw, char* lds) {
;     ...
;     for (int r = 0; r < 16; ++r) { float s = 0.f;
; #pragma unroll
;       for (int d0 = 0; d0 < 4; ++d0) { const float v = o[d0][r] * rli[r] - X[(d0 * 16 + r) * 64 + lane]; o[d0][r] = v; s += v * v; }
;       s += __shfl_xor(s, 1); s += __shfl_xor(s, 2); s += __shfl_xor(s, 4); s += __shfl_xor(s, 8); s += __shfl_xor(s, 16);
;       const float rs = __builtin_amdgcn_rsqf(s * (1.f / 128.f) + 1e-6f); const int orow = crow(r, hi);
; #pragma unroll
;       for (int d0 = 0; d0 < 4; ++d0) stg[orow * 128 + d0 * 32 + r32] = __float2bfloat16(o[d0][r] * rs * g[d0]); }
	s_nop 1
	v_add_f32_dpp v2, v2, v2 row_half_mirror row_mask:0xf bank_mask:0xf
	s_waitcnt lgkmcnt(0)
	s_nop 1
	v_add_f32_dpp v2, v2, v2 row_mirror row_mask:0xf bank_mask:0xf
	ds_bpermute_b32 v5, v208, v2
	s_waitcnt lgkmcnt(0)
	v_add_f32_e32 v2, v2, v5
	v_fmamk_f32 v2, v2, 0x3c000000, v194
	v_rsq_f32_e32 v2, v2
	s_nop 0
	v_mul_f32_e32 v0, v0, v2
	v_mul_f32_e32 v0, v64, v0
	v_cvt_pk_bf16_f32 v0, v0, s0
	ds_write_b16 v68, v0 offset:4864
	v_mul_f32_e32 v0, v1, v2
	v_mul_f32_e32 v0, v65, v0
	v_cvt_pk_bf16_f32 v0, v0, s0
	ds_write_b16 v68, v0 offset:4928
	v_mul_f32_e32 v0, v3, v2
	v_mul_f32_e32 v0, v66, v0
	v_cvt_pk_bf16_f32 v0, v0, s0
	ds_write_b16 v68, v0 offset:4992
	v_mul_f32_e32 v0, v4, v2
	v_mul_f32_e32 v0, v67, v0
	v_cvt_pk_bf16_f32 v0, v0, s0
	ds_write_b16 v68, v0 offset:5056
	ds_read2st64_b32 v[0:1], v136 offset0:12 offset1:13
	ds_read2st64_b32 v[2:3], v136 offset0:28 offset1:29
	ds_read2st64_b32 v[4:5], v136 offset0:44 offset1:45
	s_waitcnt lgkmcnt(0)
	v_fma_f32 v0, v12, v138, -v0
	s_waitcnt lgkmcnt(0)
	v_fma_f32 v2, v60, v138, -v2
	v_mul_f32_e32 v8, v2, v2
	v_fmac_f32_e32 v8, v0, v0
	s_waitcnt lgkmcnt(0)
	v_fma_f32 v4, v44, v138, -v4
	v_fmac_f32_e32 v8, v4, v4
	v_fmac_f32_e32 v8, v6, v6
	s_waitcnt lgkmcnt(0)
	s_nop 1
	v_add_f32_dpp v8, v8, v8 quad_perm:[1,0,3,2] row_mask:0xf bank_mask:0xf
	s_waitcnt lgkmcnt(0)
	s_nop 1
	v_add_f32_dpp v8, v8, v8 quad_perm:[2,3,0,1] row_mask:0xf bank_mask:0xf
	s_waitcnt lgkmcnt(0)
	s_nop 1
	v_add_f32_dpp v8, v8, v8 row_half_mirror row_mask:0xf bank_mask:0xf
	s_waitcnt lgkmcnt(0)
	s_nop 1
	v_add_f32_dpp v8, v8, v8 row_mirror row_mask:0xf bank_mask:0xf
	ds_bpermute_b32 v9, v208, v8
	s_waitcnt lgkmcnt(0)
	v_add_f32_e32 v8, v8, v9
	v_fmamk_f32 v8, v8, 0x3c000000, v194
	v_rsq_f32_e32 v8, v8
	s_nop 0
	v_mul_f32_e32 v0, v0, v8
	v_mul_f32_e32 v0, v64, v0
	v_cvt_pk_bf16_f32 v0, v0, s0
	ds_write_b16 v68, v0 offset:6144
	v_mul_f32_e32 v0, v2, v8
	v_mul_f32_e32 v0, v65, v0
	v_cvt_pk_bf16_f32 v0, v0, s0
	ds_write_b16 v68, v0 offset:6208
	v_mul_f32_e32 v0, v4, v8
	v_mul_f32_e32 v0, v66, v0
	v_cvt_pk_bf16_f32 v0, v0, s0
	ds_write_b16 v68, v0 offset:6272
	v_mul_f32_e32 v0, v6, v8
	v_mul_f32_e32 v0, v67, v0
	v_cvt_pk_bf16_f32 v0, v0, s0
	ds_write_b16 v68, v0 offset:6336
	v_fma_f32 v0, v13, v137, -v1
	v_fma_f32 v1, v61, v137, -v3
	v_mul_f32_e32 v2, v1, v1
	v_fmac_f32_e32 v2, v0, v0
	v_fma_f32 v3, v45, v137, -v5
	v_fmac_f32_e32 v2, v3, v3
	v_fma_f32 v4, v29, v137, -v7
	v_fmac_f32_e32 v2, v4, v4
	ds_read2st64_b32 v[6:7], v136 offset0:62 offset1:63
	s_waitcnt lgkmcnt(0)
	s_nop 1
	v_add_f32_dpp v2, v2, v2 quad_perm:[1,0,3,2] row_mask:0xf bank_mask:0xf
	s_waitcnt lgkmcnt(0)
	v_fma_f32 v6, v30, v135, -v6
	s_waitcnt lgkmcnt(0)
	s_nop 1
	v_add_f32_dpp v2, v2, v2 quad_perm:[2,3,0,1] row_mask:0xf bank_mask:0xf
	s_waitcnt lgkmcnt(0)
	s_nop 1
	v_add_f32_dpp v2, v2, v2 row_half_mirror row_mask:0xf bank_mask:0xf
	s_waitcnt lgkmcnt(0)
	s_nop 1
	v_add_f32_dpp v2, v2, v2 row_mirror row_mask:0xf bank_mask:0xf
	ds_bpermute_b32 v5, v208, v2
	s_waitcnt lgkmcnt(0)
	v_add_f32_e32 v2, v2, v5
	v_fmamk_f32 v2, v2, 0x3c000000, v194
	v_rsq_f32_e32 v2, v2
	s_nop 0
	v_mul_f32_e32 v0, v0, v2
	v_mul_f32_e32 v0, v64, v0
	v_cvt_pk_bf16_f32 v0, v0, s0
	ds_write_b16 v68, v0 offset:6400
	v_mul_f32_e32 v0, v1, v2
	v_mul_f32_e32 v0, v65, v0
	v_cvt_pk_bf16_f32 v0, v0, s0
	ds_write_b16 v68, v0 offset:6464
	v_mul_f32_e32 v0, v3, v2
	v_mul_f32_e32 v0, v66, v0
	v_cvt_pk_bf16_f32 v0, v0, s0
	ds_write_b16 v68, v0 offset:6528
	v_mul_f32_e32 v0, v4, v2
	v_mul_f32_e32 v0, v67, v0
	v_cvt_pk_bf16_f32 v0, v0, s0
	ds_write_b16 v68, v0 offset:6592
	ds_read2st64_b32 v[0:1], v136 offset0:14 offset1:15
	ds_read2st64_b32 v[2:3], v136 offset0:30 offset1:31
	ds_read2st64_b32 v[4:5], v136 offset0:46 offset1:47
	s_waitcnt lgkmcnt(0)
	v_fma_f32 v0, v14, v135, -v0
	s_waitcnt lgkmcnt(0)
	v_fma_f32 v2, v62, v135, -v2
	v_mul_f32_e32 v8, v2, v2
	v_fmac_f32_e32 v8, v0, v0
	s_waitcnt lgkmcnt(0)
	v_fma_f32 v4, v46, v135, -v4
	v_fmac_f32_e32 v8, v4, v4
	v_fmac_f32_e32 v8, v6, v6
	s_waitcnt lgkmcnt(0)
	s_nop 1
	v_add_f32_dpp v8, v8, v8 quad_perm:[1,0,3,2] row_mask:0xf bank_mask:0xf
	s_waitcnt lgkmcnt(0)
; __device__ __forceinline__ int crow(int r, int hi) { return (r & 3) + 8 * (r >> 2) + 4 * hi; }
; __device__ __forceinline__ void attn_unit(const bf16* __restrict__ proj, bf16* __restrict__ cat, int b, int h, int qb, float lam, float oscale, const float* __restrict__ subln, const float* __restrict__ cw, char* lds) {
;     ...
;     for (int r = 0; r < 16; ++r) { float s = 0.f;
; #pragma unroll
;       for (int d0 = 0; d0 < 4; ++d0) { const float v = o[d0][r] * rli[r] - X[(d0 * 16 + r) * 64 + lane]; o[d0][r] = v; s += v * v; }
;       s += __shfl_xor(s, 1); s += __shfl_xor(s, 2); s += __shfl_xor(s, 4); s += __shfl_xor(s, 8); s += __shfl_xor(s, 16);
;       const float rs = __builtin_amdgcn_rsqf(s * (1.f / 128.f) + 1e-6f); const int orow = crow(r, hi);
; #pragma unroll
;       for (int d0 = 0; d0 < 4; ++d0) stg[orow * 128 + d0 * 32 + r32] = __float2bfloat16(o[d0][r] * rs * g[d0]); }
;     asm volatile("s_waitcnt lgkmcnt(0)" ::: "memory");
;     bf16* Ow = cat + (rowbase + qb * QROWS + rg * 32) * LDC + h * 128;
; #pragma unroll
;     for (int i = 0; i < 8; ++i) { const int row = i * 4 + (lane >> 4), ch = lane & 15; const u32x4 v = *(const u32x4*)(stg + row * 128 + ch * 8); *(u32x4*)(Ow + (long)row * LDC + ch * 8) = v; }
	s_nop 1
	v_add_f32_dpp v8, v8, v8 quad_perm:[2,3,0,1] row_mask:0xf bank_mask:0xf
	s_waitcnt lgkmcnt(0)
	s_nop 1
	v_add_f32_dpp v8, v8, v8 row_half_mirror row_mask:0xf bank_mask:0xf
	s_waitcnt lgkmcnt(0)
	s_nop 1
	v_add_f32_dpp v8, v8, v8 row_mirror row_mask:0xf bank_mask:0xf
	ds_bpermute_b32 v9, v208, v8
	s_waitcnt lgkmcnt(0)
	v_add_f32_e32 v8, v8, v9
	v_fmamk_f32 v8, v8, 0x3c000000, v194
	v_rsq_f32_e32 v8, v8
	s_nop 0
	v_mul_f32_e32 v0, v0, v8
	v_mul_f32_e32 v0, v64, v0
	v_cvt_pk_bf16_f32 v0, v0, s0
	ds_write_b16 v68, v0 offset:6656
	v_mul_f32_e32 v0, v2, v8
	v_mul_f32_e32 v0, v65, v0
	v_cvt_pk_bf16_f32 v0, v0, s0
	ds_write_b16 v68, v0 offset:6720
	v_mul_f32_e32 v0, v4, v8
	v_mul_f32_e32 v0, v66, v0
	v_cvt_pk_bf16_f32 v0, v0, s0
	ds_write_b16 v68, v0 offset:6784
	v_mul_f32_e32 v0, v6, v8
	v_mul_f32_e32 v0, v67, v0
	v_cvt_pk_bf16_f32 v0, v0, s0
	ds_write_b16 v68, v0 offset:6848
	v_fma_f32 v0, v15, v134, -v1
	v_fma_f32 v1, v63, v134, -v3
	v_mul_f32_e32 v2, v1, v1
	v_fmac_f32_e32 v2, v0, v0
	v_fma_f32 v3, v47, v134, -v5
	v_fmac_f32_e32 v2, v3, v3
	v_fma_f32 v4, v31, v134, -v7
	v_fmac_f32_e32 v2, v4, v4
	v_lshrrev_b32_e32 v8, 4, v177
	s_waitcnt lgkmcnt(0)
	s_nop 1
	v_add_f32_dpp v2, v2, v2 quad_perm:[1,0,3,2] row_mask:0xf bank_mask:0xf
	s_waitcnt lgkmcnt(0)
	s_nop 1
	v_add_f32_dpp v2, v2, v2 quad_perm:[2,3,0,1] row_mask:0xf bank_mask:0xf
	s_waitcnt lgkmcnt(0)
	s_nop 1
	v_add_f32_dpp v2, v2, v2 row_half_mirror row_mask:0xf bank_mask:0xf
	s_waitcnt lgkmcnt(0)
	s_nop 1
	v_add_f32_dpp v2, v2, v2 row_mirror row_mask:0xf bank_mask:0xf
	ds_bpermute_b32 v5, v208, v2
	s_waitcnt lgkmcnt(0)
	v_add_f32_e32 v2, v2, v5
	v_fmamk_f32 v2, v2, 0x3c000000, v194
	v_rsq_f32_e32 v2, v2
	s_nop 0
	v_mul_f32_e32 v0, v0, v2
	v_mul_f32_e32 v0, v64, v0
	v_cvt_pk_bf16_f32 v0, v0, s0
	ds_write_b16 v68, v0 offset:6912
	v_mul_f32_e32 v0, v1, v2
	v_mul_f32_e32 v0, v65, v0
	v_cvt_pk_bf16_f32 v0, v0, s0
	ds_write_b16 v68, v0 offset:6976
	v_mul_f32_e32 v0, v3, v2
	v_mul_f32_e32 v0, v66, v0
	v_cvt_pk_bf16_f32 v0, v0, s0
	ds_write_b16 v68, v0 offset:7040
	v_mul_f32_e32 v0, v4, v2
	v_mul_f32_e32 v0, v67, v0
	v_cvt_pk_bf16_f32 v0, v0, s0
	ds_write_b16 v68, v0 offset:7104
	v_lshlrev_b32_e32 v0, 1, v178
	v_and_b32_e32 v162, 0xf0, v0
	v_add_u32_e32 v9, s20, v162
	s_waitcnt lgkmcnt(0)
	v_lshl_add_u32 v0, v8, 8, v9
	ds_read_b128 v[0:3], v0
	v_lshl_add_u64 v[4:5], s[24:25], 0, v[162:163]
	v_lshlrev_b32_e32 v162, 12, v8
	v_lshl_add_u64 v[6:7], v[4:5], 0, v[162:163]
	s_waitcnt lgkmcnt(0)
	global_store_dwordx4 v[6:7], v[0:3], off
	v_or_b32_e32 v6, 4, v8
	s_nop 0
	v_lshl_add_u32 v0, v6, 8, v9
	ds_read_b128 v[0:3], v0
	v_lshlrev_b32_e32 v162, 12, v6
	v_lshl_add_u64 v[6:7], v[4:5], 0, v[162:163]
	s_waitcnt lgkmcnt(0)
	global_store_dwordx4 v[6:7], v[0:3], off
	v_or_b32_e32 v6, 8, v8
	s_nop 0
	v_lshl_add_u32 v0, v6, 8, v9
	ds_read_b128 v[0:3], v0
	v_lshlrev_b32_e32 v162, 12, v6
	v_lshl_add_u64 v[6:7], v[4:5], 0, v[162:163]
	s_waitcnt lgkmcnt(0)
	global_store_dwordx4 v[6:7], v[0:3], off
	v_or_b32_e32 v6, 12, v8
	s_nop 0
	v_lshl_add_u32 v0, v6, 8, v9
	ds_read_b128 v[0:3], v0
	v_lshlrev_b32_e32 v162, 12, v6
	v_lshl_add_u64 v[6:7], v[4:5], 0, v[162:163]
	s_waitcnt lgkmcnt(0)
	global_store_dwordx4 v[6:7], v[0:3], off
	v_or_b32_e32 v6, 16, v8
	s_nop 0
	v_lshl_add_u32 v0, v6, 8, v9
	ds_read_b128 v[0:3], v0
	v_lshlrev_b32_e32 v162, 12, v6
	v_lshl_add_u64 v[6:7], v[4:5], 0, v[162:163]
	s_waitcnt lgkmcnt(0)
	global_store_dwordx4 v[6:7], v[0:3], off
	v_or_b32_e32 v6, 20, v8
	s_nop 0
	v_lshl_add_u32 v0, v6, 8, v9
	ds_read_b128 v[0:3], v0
	v_lshlrev_b32_e32 v162, 12, v6
	v_lshl_add_u64 v[6:7], v[4:5], 0, v[162:163]
	s_waitcnt lgkmcnt(0)
	global_store_dwordx4 v[6:7], v[0:3], off
	v_or_b32_e32 v6, 24, v8
	s_nop 0
	v_lshl_add_u32 v0, v6, 8, v9
	ds_read_b128 v[0:3], v0
	v_lshlrev_b32_e32 v162, 12, v6
	v_lshl_add_u64 v[6:7], v[4:5], 0, v[162:163]
	s_waitcnt lgkmcnt(0)
	global_store_dwordx4 v[6:7], v[0:3], off
	v_or_b32_e32 v6, 28, v8
	s_nop 0
	v_lshl_add_u32 v0, v6, 8, v9
	ds_read_b128 v[0:3], v0
	v_lshlrev_b32_e32 v162, 12, v6
	v_lshl_add_u64 v[4:5], v[4:5], 0, v[162:163]
	s_waitcnt lgkmcnt(0)
	global_store_dwordx4 v[4:5], v[0:3], off
	s_branch .LBB0_207
